# A/B of the static attention priority raise: waves 0-3 (older half) instead of 4-7
# speedup vs baseline: 1.0052x; 1.0052x over previous
; __global__ void __launch_bounds__(512, 2) fwd_mega(Params P_by_kernarg) {
;     ...
;         __syncthreads();
;         }
;     ...
;         }
;         { att::Seam S;
;           auto mk = [&](int L, int pass) { att::BlockRef r; const int vh = L >> 3, x = L & 7, qb = pass ? 15 - x : x, b = vh >> 5, h = (vh >> 2) & 7, c = (vh >> 1) & 1, vf = vh & 1;
;               r.Q = (const att::bf16*)(Qb + ((size_t)(b * TPAD + NMETA + qb * 256)) * 2048 + h * 256 + c * 128);
;               r.K = (const att::bf16*)(Kb + ((size_t)b * TPAD) * 2048 + h * 256 + c * 128);
;               r.V = (const att::bf16*)(Vb + ((size_t)b * TPAD) * 2048 + h * 256 + vf * 128);
;               r.O = (att::bf16*)(Opart + (size_t)c * MX * 2048 + ((size_t)(b * 4096 + qb * 256)) * 2048 + h * 256 + vf * 128);
;               r.P0 = NMETA + qb * 256; return r; };
;           int L = vcu;
;           if (L < 512) {
;               int pass = 0; att::BlockRef cur = mk(L, 0);
;               att::prime(cur, (char*)lds, S);
.LBB0_375:
	s_cmpk_lt_i32 s67, 0x200
	s_waitcnt lgkmcnt(0)
	s_barrier
	s_cbranch_scc0 .LBB0_543
	s_cmp_ge_u32 s66, 4
	s_cbranch_scc1 .Lattn_prio_done
	s_setprio 1
